# half of the workgroups run their HGRN scan share before MoBA/mem units (overlap bandwidth-bound scan with compute-bound attention)
# speedup vs baseline: 1.0225x; 1.0074x over previous
; #define LAS __attribute__((address_space(3)))
; __global__ void __launch_bounds__(512) hymba_fwd(Args a) {
;     ...
;         if (IN(base + 2)) {
;             { const int lane = threadIdx.x & 63;
;               float xq = fabsf(a.mqn[l * 64 + lane]), xk = fabsf(a.mkn[l * 64 + lane]);
;               float yq = fmaxf(fabsf(a.memqn[l * 128 + lane]), fabsf(a.memqn[l * 128 + 64 + lane])), yk = fmaxf(fabsf(a.memkn[l * 128 + lane]), fabsf(a.memkn[l * 128 + 64 + lane]));
; #pragma unroll
;               for (int ofs = 1; ofs < 64; ofs <<= 1) { xq = fmaxf(xq, __shfl_xor(xq, ofs)); xk = fmaxf(xk, __shfl_xor(xk, ofs)); yq = fmaxf(yq, __shfl_xor(yq, ofs)); yk = fmaxf(yk, __shfl_xor(yk, ofs)); }
;               if (threadIdx.x == 0) { ((LAS float*)(lds + 80000))[0] = xq * xk * (8.f * 1.03f * LOG2E); ((LAS float*)(lds + 80000))[1] = yq * yk * (11.3137085f * 1.03f * LOG2E); }
;               __syncthreads(); }
;             {
;                 for (int u = bx; u < 512; u += G) {
;                     int bh, qb; if (G == 256) { const int v = (bx & 7) * 32 + (bx >> 3);
;                         bh = v >> 2; const int s = v & 3; qb = (u < 256) ? 7 - s : s; } else { bh = u >> 3; qb = 7 - (u & 7); }
;                     moba_unit(a, l, lds, bh >> 3, bh & 7, qb);
;                 }
;             }
;             for (int u0 = bx; u0 < 256; u0 += G) { const int u = (G == 256) ? (u0 & 7) * 32 + (u0 >> 3) : u0;
;                 mem_unit(a, l, lds, u >> 5, (u >> 3) & 3, u & 7); }
;             hgrn_scan_phase(a);
;             __syncthreads();
;         }
.LBB0_516:
	s_or_b64 exec, exec, s[14:15]
	v_readlane_b32 s4, v245, 47
	v_readlane_b32 s5, v245, 48
	s_andn2_b64 vcc, exec, s[4:5]
	s_mov_b32 s18, s2
	s_waitcnt lgkmcnt(0)
	s_barrier
	s_mov_b32 s98, 0
	s_bitcmp1_b32 s2, 3
	s_cbranch_scc0 .Lx2_noearly
	s_cmp_eq_u32 s3, 0x100
	s_cbranch_scc0 .Lx2_noearly
	s_mov_b32 s98, 1
	s_branch .LBB0_522
.Lx2_back:
	v_readlane_b32 s4, v245, 47
	v_readlane_b32 s5, v245, 48
	s_nop 0
	s_andn2_b64 vcc, exec, s[4:5]
.Lx2_noearly:
	s_cbranch_vccz .LBB0_544

; __device__ __forceinline__ int otid() { int t = threadIdx.x; asm volatile("" : "+v"(t)); return t; }
; __device__ __forceinline__ void hgrn_scan_phase(const Args& a) {
;     const int id = blockIdx.x * 512 + otid(), NT = gridDim.x * 512;
;     for (int it = id; it < 32 * 128 * 32; it += NT) {
;         const int bh = it >> 12, dv = (it >> 5) & 127, dkc = it & 31;
;         u32x2* st = (u32x2*)((bf16_t*)(a.ws + WS_H) + (size_t)bh * 32 * 16384 + dv * 128 + dkc * 4);
;         const f32x4* dc = (const f32x4*)((const float*)(a.ws + WS_DECAY) + (size_t)bh * 32 * 128 + dkc * 4);
.LBB0_522:
	s_cmp_eq_u32 s98, 2
	s_cbranch_scc1 .Lx2_end
	v_mov_b32_e32 v0, v178
	v_readlane_b32 s4, v245, 54
	s_nop 1
	v_add_u32_e32 v12, s4, v0
	s_mov_b32 s4, 0x20000
	v_cmp_gt_i32_e32 vcc, s4, v12
	s_and_saveexec_b64 s[40:41], vcc
	v_readlane_b32 s6, v245, 55
	s_cbranch_execz .LBB0_527
	s_nop 1
	s_cmp_eq_u32 s6, 0x20000
	s_cbranch_scc1 .Lscan_fast
	v_readlane_b32 s4, v244, 44
	s_mov_b64 s[42:43], 0
	s_nop 0
	v_lshl_add_u32 v13, v0, 2, s4

; #define SEAM(k) do { if (IN(k) && IN((k) + 1)) { if (a.pad == 0x5eed) cg::this_grid().sync(); xcd_barrier(xbar); } } while (0)
; __global__ void __launch_bounds__(512) hymba_fwd(Args a) {
;     ...
;             hgrn_scan_phase(a);
;             __syncthreads();
;         }
;         SEAM(base + 2);
.LBB0_527:
	s_or_b64 exec, exec, s[40:41]
	s_cmp_eq_u32 s98, 1
	s_cbranch_scc1 .Lx2_ret
.Lx2_end:
	v_readlane_b32 s4, v244, 60
	v_readlane_b32 s8, v246, 0
	s_add_i32 s4, s4, 4
	v_readlane_b32 s9, v246, 1
	s_cmp_lt_i32 s4, s9
	s_barrier
	s_cbranch_scc0 .LBB0_634
	s_and_b64 vcc, exec, s[96:97]
	s_cbranch_vccnz .LBB0_540
	s_barrier
	s_mov_b64 s[14:15], exec
	v_readlane_b32 s8, v244, 4
	v_readlane_b32 s9, v244, 5
	s_and_b64 s[8:9], s[14:15], s[8:9]
	s_mov_b64 exec, s[8:9]
	s_cbranch_execz .LBB0_539
	v_readlane_b32 s8, v246, 2
	v_readlane_b32 s9, v246, 3
	buffer_wbl2 sc1
	s_waitcnt vmcnt(0)
	s_load_dwordx2 s[16:17], s[8:9], 0x58
	s_mov_b64 s[18:19], exec
	v_mbcnt_lo_u32_b32 v1, s18, 0
	v_mbcnt_hi_u32_b32 v1, s19, v1
	v_cmp_eq_u32_e32 vcc, 0, v1
	s_waitcnt lgkmcnt(0)
	global_load_dword v0, v145, s[16:17] offset:40
	s_and_saveexec_b64 s[40:41], vcc
	s_cbranch_execz .LBB0_532
	s_bcnt1_i32_b64 s5, s[18:19]
	v_mov_b32_e32 v2, s5
	global_atomic_add v2, v145, v2, s[16:17] offset:32 sc0

; __device__ __forceinline__ unsigned pk2(float lo, float hi) { f32x2_t v = {lo, hi}; bf16x2_t b = __builtin_convertvector(v, bf16x2_t); return __builtin_bit_cast(unsigned, b); }
; __device__ __forceinline__ float bflo(unsigned u) { return __uint_as_float(u << 16); }
; __device__ __forceinline__ float bfhi(unsigned u) { return __uint_as_float(u & 0xffff0000u); }
; __device__ __forceinline__ int otid() { int t = threadIdx.x; asm volatile("" : "+v"(t)); return t; }
; __device__ __forceinline__ void hgrn_scan_phase(const Args& a) {
;     const int id = blockIdx.x * 512 + otid(), NT = gridDim.x * 512;
;     for (int it = id; it < 32 * 128 * 32; it += NT) {
;         const int bh = it >> 12, dv = (it >> 5) & 127, dkc = it & 31;
;         u32x2* st = (u32x2*)((bf16_t*)(a.ws + WS_H) + (size_t)bh * 32 * 16384 + dv * 128 + dkc * 4);
;         const f32x4* dc = (const f32x4*)((const float*)(a.ws + WS_DECAY) + (size_t)bh * 32 * 128 + dkc * 4);
;         float r0 = 0.f, r1 = 0.f, r2 = 0.f, r3 = 0.f;
; #pragma unroll 8
;         for (int c = 0; c < 32; ++c) {
;             const u32x2 u = st[(size_t)c * 4096]; const f32x4 dd = dc[c * 32];
;             u32x2 o; o.x = pk2(r0, r1); o.y = pk2(r2, r3); st[(size_t)c * 4096] = o;
;             r0 = dd.x * r0 + bflo(u.x); r1 = dd.y * r1 + bfhi(u.x); r2 = dd.z * r2 + bflo(u.y); r3 = dd.w * r3 + bfhi(u.y);
;         }
;     }
; }
.Lscan_fast:
	v_lshrrev_b32_e32 v222, 12, v12
	v_and_b32_e32 v220, 0xfff, v12
	v_bfe_u32 v221, v12, 5, 4
	v_and_b32_e32 v216, 1, v12
	v_lshl_or_b32 v221, v221, 1, v216
	v_lshlrev_b32_e32 v220, 3, v220
	v_lshlrev_b32_e32 v221, 4, v221
	v_lshl_or_b32 v220, v222, 20, v220
	v_lshl_or_b32 v221, v222, 14, v221
	s_add_u32 s10, s78, 0x1e00000
	s_addc_u32 s11, s79, 0
	s_mov_b32 s14, s10
	s_mov_b32 s15, s11
	s_add_u32 s8, s78, 0xf620000
	s_addc_u32 s9, s79, 0
	v_mov_b32_e32 v208, 0
	v_mov_b32_e32 v209, 0
	v_mov_b32_e32 v210, 0
	v_mov_b32_e32 v211, 0
	global_load_dwordx2 v[128:129], v220, s[10:11]
	s_add_u32 s10, s10, 0x8000
	s_addc_u32 s11, s11, 0
	global_load_dwordx4 v[12:15], v221, s[8:9]
	global_load_dwordx2 v[130:131], v220, s[10:11]
	s_add_u32 s10, s10, 0x8000
	s_addc_u32 s11, s11, 0
	global_load_dwordx4 v[16:19], v221, s[8:9] offset:512
	global_load_dwordx2 v[132:133], v220, s[10:11]
	s_add_u32 s10, s10, 0x8000
	s_addc_u32 s11, s11, 0
	global_load_dwordx4 v[20:23], v221, s[8:9] offset:1024
	global_load_dwordx2 v[134:135], v220, s[10:11]
	s_add_u32 s10, s10, 0x8000
	s_addc_u32 s11, s11, 0
	global_load_dwordx4 v[24:27], v221, s[8:9] offset:1536
	global_load_dwordx2 v[136:137], v220, s[10:11]
	s_add_u32 s10, s10, 0x8000
	s_addc_u32 s11, s11, 0
	global_load_dwordx4 v[28:31], v221, s[8:9] offset:2048
	global_load_dwordx2 v[138:139], v220, s[10:11]
	s_add_u32 s10, s10, 0x8000
	s_addc_u32 s11, s11, 0
	global_load_dwordx4 v[32:35], v221, s[8:9] offset:2560
	global_load_dwordx2 v[140:141], v220, s[10:11]
	s_add_u32 s10, s10, 0x8000
	s_addc_u32 s11, s11, 0
	global_load_dwordx4 v[36:39], v221, s[8:9] offset:3072
	global_load_dwordx2 v[142:143], v220, s[10:11]
	s_add_u32 s10, s10, 0x8000
	s_addc_u32 s11, s11, 0
	global_load_dwordx4 v[40:43], v221, s[8:9] offset:3584
	s_add_u32 s8, s8, 0x1000
	s_addc_u32 s9, s9, 0
	global_load_dwordx2 v[156:157], v220, s[10:11]
	s_add_u32 s10, s10, 0x8000
	s_addc_u32 s11, s11, 0
	global_load_dwordx4 v[44:47], v221, s[8:9]
	global_load_dwordx2 v[158:159], v220, s[10:11]
	s_add_u32 s10, s10, 0x8000
	s_addc_u32 s11, s11, 0
	global_load_dwordx4 v[48:51], v221, s[8:9] offset:512
	global_load_dwordx2 v[160:161], v220, s[10:11]
	s_add_u32 s10, s10, 0x8000
	s_addc_u32 s11, s11, 0
	global_load_dwordx4 v[52:55], v221, s[8:9] offset:1024
	global_load_dwordx2 v[162:163], v220, s[10:11]
	s_add_u32 s10, s10, 0x8000
	s_addc_u32 s11, s11, 0
	global_load_dwordx4 v[56:59], v221, s[8:9] offset:1536
	global_load_dwordx2 v[164:165], v220, s[10:11]
	s_add_u32 s10, s10, 0x8000
	s_addc_u32 s11, s11, 0
	global_load_dwordx4 v[60:63], v221, s[8:9] offset:2048
	global_load_dwordx2 v[166:167], v220, s[10:11]
	s_add_u32 s10, s10, 0x8000
	s_addc_u32 s11, s11, 0
	global_load_dwordx4 v[64:67], v221, s[8:9] offset:2560
	global_load_dwordx2 v[168:169], v220, s[10:11]
	s_add_u32 s10, s10, 0x8000
	s_addc_u32 s11, s11, 0
	global_load_dwordx4 v[68:71], v221, s[8:9] offset:3072
	global_load_dwordx2 v[172:173], v220, s[10:11]
	s_add_u32 s10, s10, 0x8000
	s_addc_u32 s11, s11, 0
	global_load_dwordx4 v[72:75], v221, s[8:9] offset:3584
	s_add_u32 s8, s8, 0x1000
	s_addc_u32 s9, s9, 0
	global_load_dwordx2 v[174:175], v220, s[10:11]
	s_add_u32 s10, s10, 0x8000
	s_addc_u32 s11, s11, 0
	global_load_dwordx4 v[76:79], v221, s[8:9]
	global_load_dwordx2 v[224:225], v220, s[10:11]
	s_add_u32 s10, s10, 0x8000
	s_addc_u32 s11, s11, 0
	global_load_dwordx4 v[84:87], v221, s[8:9] offset:512
	global_load_dwordx2 v[200:201], v220, s[10:11]
	s_add_u32 s10, s10, 0x8000
	s_addc_u32 s11, s11, 0
	global_load_dwordx4 v[88:91], v221, s[8:9] offset:1024
	global_load_dwordx2 v[202:203], v220, s[10:11]
	s_add_u32 s10, s10, 0x8000
	s_addc_u32 s11, s11, 0
	global_load_dwordx4 v[92:95], v221, s[8:9] offset:1536
	global_load_dwordx2 v[204:205], v220, s[10:11]
	s_add_u32 s10, s10, 0x8000
	s_addc_u32 s11, s11, 0
	global_load_dwordx4 v[100:103], v221, s[8:9] offset:2048
	global_load_dwordx2 v[206:207], v220, s[10:11]
	s_add_u32 s10, s10, 0x8000
	s_addc_u32 s11, s11, 0
	global_load_dwordx4 v[104:107], v221, s[8:9] offset:2560
	global_load_dwordx2 v[226:227], v220, s[10:11]
	s_add_u32 s10, s10, 0x8000
	s_addc_u32 s11, s11, 0
	global_load_dwordx4 v[108:111], v221, s[8:9] offset:3072
	global_load_dwordx2 v[228:229], v220, s[10:11]
	s_add_u32 s10, s10, 0x8000
	s_addc_u32 s11, s11, 0
	global_load_dwordx4 v[112:115], v221, s[8:9] offset:3584
	s_add_u32 s8, s8, 0x1000
	s_addc_u32 s9, s9, 0
	v_cvt_pk_bf16_f32 v216, v208, v209
	v_cvt_pk_bf16_f32 v217, v210, v211
	global_store_dwordx2 v220, v[216:217], s[14:15]
	s_add_u32 s14, s14, 0x8000
	s_addc_u32 s15, s15, 0
	s_waitcnt vmcnt(48)
	v_lshlrev_b32_e32 v212, 16, v128
	v_and_b32_e32 v213, 0xffff0000, v128
	v_lshlrev_b32_e32 v214, 16, v129
	v_and_b32_e32 v215, 0xffff0000, v129
	s_waitcnt vmcnt(47)
	v_pk_fma_f32 v[208:209], v[208:209], v[12:13], v[212:213]
	v_pk_fma_f32 v[210:211], v[210:211], v[14:15], v[214:215]
	global_load_dwordx2 v[128:129], v220, s[10:11]
	s_add_u32 s10, s10, 0x8000
	s_addc_u32 s11, s11, 0
	global_load_dwordx4 v[12:15], v221, s[8:9]
	v_cvt_pk_bf16_f32 v218, v208, v209
	v_cvt_pk_bf16_f32 v219, v210, v211
	global_store_dwordx2 v220, v[218:219], s[14:15]
	s_add_u32 s14, s14, 0x8000
	s_addc_u32 s15, s15, 0
	s_waitcnt vmcnt(49)
	v_lshlrev_b32_e32 v212, 16, v130
	v_and_b32_e32 v213, 0xffff0000, v130
	v_lshlrev_b32_e32 v214, 16, v131
	v_and_b32_e32 v215, 0xffff0000, v131
	s_waitcnt vmcnt(48)
	v_pk_fma_f32 v[208:209], v[208:209], v[16:17], v[212:213]
	v_pk_fma_f32 v[210:211], v[210:211], v[18:19], v[214:215]
	global_load_dwordx2 v[130:131], v220, s[10:11]
	s_add_u32 s10, s10, 0x8000
	s_addc_u32 s11, s11, 0
	global_load_dwordx4 v[16:19], v221, s[8:9] offset:512
	v_cvt_pk_bf16_f32 v216, v208, v209
	v_cvt_pk_bf16_f32 v217, v210, v211
	global_store_dwordx2 v220, v[216:217], s[14:15]
	s_add_u32 s14, s14, 0x8000
	s_addc_u32 s15, s15, 0
	s_waitcnt vmcnt(50)
; __device__ __forceinline__ unsigned pk2(float lo, float hi) { f32x2_t v = {lo, hi}; bf16x2_t b = __builtin_convertvector(v, bf16x2_t); return __builtin_bit_cast(unsigned, b); }
; __device__ __forceinline__ float bflo(unsigned u) { return __uint_as_float(u << 16); }
; __device__ __forceinline__ float bfhi(unsigned u) { return __uint_as_float(u & 0xffff0000u); }
; __device__ __forceinline__ void hgrn_scan_phase(const Args& a) {
;     ...
;         for (int c = 0; c < 32; ++c) {
;             const u32x2 u = st[(size_t)c * 4096]; const f32x4 dd = dc[c * 32];
;             u32x2 o; o.x = pk2(r0, r1); o.y = pk2(r2, r3); st[(size_t)c * 4096] = o;
;             r0 = dd.x * r0 + bflo(u.x); r1 = dd.y * r1 + bfhi(u.x); r2 = dd.z * r2 + bflo(u.y); r3 = dd.w * r3 + bfhi(u.y);
;         }
	v_lshlrev_b32_e32 v212, 16, v132
	v_and_b32_e32 v213, 0xffff0000, v132
	v_lshlrev_b32_e32 v214, 16, v133
	v_and_b32_e32 v215, 0xffff0000, v133
	s_waitcnt vmcnt(49)
	v_pk_fma_f32 v[208:209], v[208:209], v[20:21], v[212:213]
	v_pk_fma_f32 v[210:211], v[210:211], v[22:23], v[214:215]
	global_load_dwordx2 v[132:133], v220, s[10:11]
	s_add_u32 s10, s10, 0x8000
	s_addc_u32 s11, s11, 0
	global_load_dwordx4 v[20:23], v221, s[8:9] offset:1024
	v_cvt_pk_bf16_f32 v218, v208, v209
	v_cvt_pk_bf16_f32 v219, v210, v211
	global_store_dwordx2 v220, v[218:219], s[14:15]
	s_add_u32 s14, s14, 0x8000
	s_addc_u32 s15, s15, 0
	s_waitcnt vmcnt(51)
	v_lshlrev_b32_e32 v212, 16, v134
	v_and_b32_e32 v213, 0xffff0000, v134
	v_lshlrev_b32_e32 v214, 16, v135
	v_and_b32_e32 v215, 0xffff0000, v135
	s_waitcnt vmcnt(50)
	v_pk_fma_f32 v[208:209], v[208:209], v[24:25], v[212:213]
	v_pk_fma_f32 v[210:211], v[210:211], v[26:27], v[214:215]
	global_load_dwordx2 v[134:135], v220, s[10:11]
	s_add_u32 s10, s10, 0x8000
	s_addc_u32 s11, s11, 0
	global_load_dwordx4 v[24:27], v221, s[8:9] offset:1536
	v_cvt_pk_bf16_f32 v216, v208, v209
	v_cvt_pk_bf16_f32 v217, v210, v211
	global_store_dwordx2 v220, v[216:217], s[14:15]
	s_add_u32 s14, s14, 0x8000
	s_addc_u32 s15, s15, 0
	s_waitcnt vmcnt(52)
	v_lshlrev_b32_e32 v212, 16, v136
	v_and_b32_e32 v213, 0xffff0000, v136
	v_lshlrev_b32_e32 v214, 16, v137
	v_and_b32_e32 v215, 0xffff0000, v137
	s_waitcnt vmcnt(51)
	v_pk_fma_f32 v[208:209], v[208:209], v[28:29], v[212:213]
	v_pk_fma_f32 v[210:211], v[210:211], v[30:31], v[214:215]
	global_load_dwordx2 v[136:137], v220, s[10:11]
	s_add_u32 s10, s10, 0x8000
	s_addc_u32 s11, s11, 0
	global_load_dwordx4 v[28:31], v221, s[8:9] offset:2048
	v_cvt_pk_bf16_f32 v218, v208, v209
	v_cvt_pk_bf16_f32 v219, v210, v211
	global_store_dwordx2 v220, v[218:219], s[14:15]
	s_add_u32 s14, s14, 0x8000
	s_addc_u32 s15, s15, 0
	s_waitcnt vmcnt(53)
	v_lshlrev_b32_e32 v212, 16, v138
	v_and_b32_e32 v213, 0xffff0000, v138
	v_lshlrev_b32_e32 v214, 16, v139
	v_and_b32_e32 v215, 0xffff0000, v139
	s_waitcnt vmcnt(52)
	v_pk_fma_f32 v[208:209], v[208:209], v[32:33], v[212:213]
	v_pk_fma_f32 v[210:211], v[210:211], v[34:35], v[214:215]
	global_load_dwordx2 v[138:139], v220, s[10:11]
	s_add_u32 s10, s10, 0x8000
	s_addc_u32 s11, s11, 0
	global_load_dwordx4 v[32:35], v221, s[8:9] offset:2560
	v_cvt_pk_bf16_f32 v216, v208, v209
	v_cvt_pk_bf16_f32 v217, v210, v211
	global_store_dwordx2 v220, v[216:217], s[14:15]
	s_add_u32 s14, s14, 0x8000
	s_addc_u32 s15, s15, 0
	s_waitcnt vmcnt(54)
	v_lshlrev_b32_e32 v212, 16, v140
	v_and_b32_e32 v213, 0xffff0000, v140
	v_lshlrev_b32_e32 v214, 16, v141
	v_and_b32_e32 v215, 0xffff0000, v141
	s_waitcnt vmcnt(53)
	v_pk_fma_f32 v[208:209], v[208:209], v[36:37], v[212:213]
	v_pk_fma_f32 v[210:211], v[210:211], v[38:39], v[214:215]
	global_load_dwordx2 v[140:141], v220, s[10:11]
	s_add_u32 s10, s10, 0x8000
	s_addc_u32 s11, s11, 0
	global_load_dwordx4 v[36:39], v221, s[8:9] offset:3072
	v_cvt_pk_bf16_f32 v218, v208, v209
	v_cvt_pk_bf16_f32 v219, v210, v211
	global_store_dwordx2 v220, v[218:219], s[14:15]
	s_add_u32 s14, s14, 0x8000
	s_addc_u32 s15, s15, 0
	s_waitcnt vmcnt(55)
	v_lshlrev_b32_e32 v212, 16, v142
	v_and_b32_e32 v213, 0xffff0000, v142
	v_lshlrev_b32_e32 v214, 16, v143
	v_and_b32_e32 v215, 0xffff0000, v143
	s_waitcnt vmcnt(54)
	v_pk_fma_f32 v[208:209], v[208:209], v[40:41], v[212:213]
	v_pk_fma_f32 v[210:211], v[210:211], v[42:43], v[214:215]
	global_load_dwordx2 v[142:143], v220, s[10:11]
	s_add_u32 s10, s10, 0x8000
	s_addc_u32 s11, s11, 0
	global_load_dwordx4 v[40:43], v221, s[8:9] offset:3584
	s_add_u32 s8, s8, 0x1000
	s_addc_u32 s9, s9, 0
	v_cvt_pk_bf16_f32 v216, v208, v209
	v_cvt_pk_bf16_f32 v217, v210, v211
	global_store_dwordx2 v220, v[216:217], s[14:15]
	s_add_u32 s14, s14, 0x8000
	s_addc_u32 s15, s15, 0
	s_waitcnt vmcnt(56)
	v_lshlrev_b32_e32 v212, 16, v156
	v_and_b32_e32 v213, 0xffff0000, v156
	v_lshlrev_b32_e32 v214, 16, v157
	v_and_b32_e32 v215, 0xffff0000, v157
	s_waitcnt vmcnt(55)
	v_pk_fma_f32 v[208:209], v[208:209], v[44:45], v[212:213]
	v_pk_fma_f32 v[210:211], v[210:211], v[46:47], v[214:215]
	v_cvt_pk_bf16_f32 v218, v208, v209
	v_cvt_pk_bf16_f32 v219, v210, v211
	global_store_dwordx2 v220, v[218:219], s[14:15]
	s_add_u32 s14, s14, 0x8000
	s_addc_u32 s15, s15, 0
	s_waitcnt vmcnt(55)
	v_lshlrev_b32_e32 v212, 16, v158
	v_and_b32_e32 v213, 0xffff0000, v158
	v_lshlrev_b32_e32 v214, 16, v159
	v_and_b32_e32 v215, 0xffff0000, v159
	s_waitcnt vmcnt(54)
	v_pk_fma_f32 v[208:209], v[208:209], v[48:49], v[212:213]
	v_pk_fma_f32 v[210:211], v[210:211], v[50:51], v[214:215]
	v_cvt_pk_bf16_f32 v216, v208, v209
	v_cvt_pk_bf16_f32 v217, v210, v211
	global_store_dwordx2 v220, v[216:217], s[14:15]
	s_add_u32 s14, s14, 0x8000
	s_addc_u32 s15, s15, 0
	s_waitcnt vmcnt(54)
	v_lshlrev_b32_e32 v212, 16, v160
	v_and_b32_e32 v213, 0xffff0000, v160
	v_lshlrev_b32_e32 v214, 16, v161
	v_and_b32_e32 v215, 0xffff0000, v161
	s_waitcnt vmcnt(53)
	v_pk_fma_f32 v[208:209], v[208:209], v[52:53], v[212:213]
	v_pk_fma_f32 v[210:211], v[210:211], v[54:55], v[214:215]
	v_cvt_pk_bf16_f32 v218, v208, v209
	v_cvt_pk_bf16_f32 v219, v210, v211
	global_store_dwordx2 v220, v[218:219], s[14:15]
	s_add_u32 s14, s14, 0x8000
	s_addc_u32 s15, s15, 0
	s_waitcnt vmcnt(53)
	v_lshlrev_b32_e32 v212, 16, v162
	v_and_b32_e32 v213, 0xffff0000, v162
	v_lshlrev_b32_e32 v214, 16, v163
	v_and_b32_e32 v215, 0xffff0000, v163
	s_waitcnt vmcnt(52)
	v_pk_fma_f32 v[208:209], v[208:209], v[56:57], v[212:213]
	v_pk_fma_f32 v[210:211], v[210:211], v[58:59], v[214:215]
	v_cvt_pk_bf16_f32 v216, v208, v209
	v_cvt_pk_bf16_f32 v217, v210, v211
	global_store_dwordx2 v220, v[216:217], s[14:15]
	s_add_u32 s14, s14, 0x8000
	s_addc_u32 s15, s15, 0
	s_waitcnt vmcnt(52)
; __device__ __forceinline__ unsigned pk2(float lo, float hi) { f32x2_t v = {lo, hi}; bf16x2_t b = __builtin_convertvector(v, bf16x2_t); return __builtin_bit_cast(unsigned, b); }
; __device__ __forceinline__ float bflo(unsigned u) { return __uint_as_float(u << 16); }
; __device__ __forceinline__ float bfhi(unsigned u) { return __uint_as_float(u & 0xffff0000u); }
; __device__ __forceinline__ void hgrn_scan_phase(const Args& a) {
;     ...
;         for (int c = 0; c < 32; ++c) {
;             const u32x2 u = st[(size_t)c * 4096]; const f32x4 dd = dc[c * 32];
;             u32x2 o; o.x = pk2(r0, r1); o.y = pk2(r2, r3); st[(size_t)c * 4096] = o;
;             r0 = dd.x * r0 + bflo(u.x); r1 = dd.y * r1 + bfhi(u.x); r2 = dd.z * r2 + bflo(u.y); r3 = dd.w * r3 + bfhi(u.y);
;         }
	v_lshlrev_b32_e32 v212, 16, v164
	v_and_b32_e32 v213, 0xffff0000, v164
	v_lshlrev_b32_e32 v214, 16, v165
	v_and_b32_e32 v215, 0xffff0000, v165
	s_waitcnt vmcnt(51)
	v_pk_fma_f32 v[208:209], v[208:209], v[60:61], v[212:213]
	v_pk_fma_f32 v[210:211], v[210:211], v[62:63], v[214:215]
	v_cvt_pk_bf16_f32 v218, v208, v209
	v_cvt_pk_bf16_f32 v219, v210, v211
	global_store_dwordx2 v220, v[218:219], s[14:15]
	s_add_u32 s14, s14, 0x8000
	s_addc_u32 s15, s15, 0
	s_waitcnt vmcnt(51)
	v_lshlrev_b32_e32 v212, 16, v166
	v_and_b32_e32 v213, 0xffff0000, v166
	v_lshlrev_b32_e32 v214, 16, v167
	v_and_b32_e32 v215, 0xffff0000, v167
	s_waitcnt vmcnt(50)
	v_pk_fma_f32 v[208:209], v[208:209], v[64:65], v[212:213]
	v_pk_fma_f32 v[210:211], v[210:211], v[66:67], v[214:215]
	v_cvt_pk_bf16_f32 v216, v208, v209
	v_cvt_pk_bf16_f32 v217, v210, v211
	global_store_dwordx2 v220, v[216:217], s[14:15]
	s_add_u32 s14, s14, 0x8000
	s_addc_u32 s15, s15, 0
	s_waitcnt vmcnt(50)
	v_lshlrev_b32_e32 v212, 16, v168
	v_and_b32_e32 v213, 0xffff0000, v168
	v_lshlrev_b32_e32 v214, 16, v169
	v_and_b32_e32 v215, 0xffff0000, v169
	s_waitcnt vmcnt(49)
	v_pk_fma_f32 v[208:209], v[208:209], v[68:69], v[212:213]
	v_pk_fma_f32 v[210:211], v[210:211], v[70:71], v[214:215]
	v_cvt_pk_bf16_f32 v218, v208, v209
	v_cvt_pk_bf16_f32 v219, v210, v211
	global_store_dwordx2 v220, v[218:219], s[14:15]
	s_add_u32 s14, s14, 0x8000
	s_addc_u32 s15, s15, 0
	s_waitcnt vmcnt(49)
	v_lshlrev_b32_e32 v212, 16, v172
	v_and_b32_e32 v213, 0xffff0000, v172
	v_lshlrev_b32_e32 v214, 16, v173
	v_and_b32_e32 v215, 0xffff0000, v173
	s_waitcnt vmcnt(48)
	v_pk_fma_f32 v[208:209], v[208:209], v[72:73], v[212:213]
	v_pk_fma_f32 v[210:211], v[210:211], v[74:75], v[214:215]
	v_cvt_pk_bf16_f32 v216, v208, v209
	v_cvt_pk_bf16_f32 v217, v210, v211
	global_store_dwordx2 v220, v[216:217], s[14:15]
	s_add_u32 s14, s14, 0x8000
	s_addc_u32 s15, s15, 0
	s_waitcnt vmcnt(48)
	v_lshlrev_b32_e32 v212, 16, v174
	v_and_b32_e32 v213, 0xffff0000, v174
	v_lshlrev_b32_e32 v214, 16, v175
	v_and_b32_e32 v215, 0xffff0000, v175
	s_waitcnt vmcnt(47)
	v_pk_fma_f32 v[208:209], v[208:209], v[76:77], v[212:213]
	v_pk_fma_f32 v[210:211], v[210:211], v[78:79], v[214:215]
	v_cvt_pk_bf16_f32 v218, v208, v209
	v_cvt_pk_bf16_f32 v219, v210, v211
	global_store_dwordx2 v220, v[218:219], s[14:15]
	s_add_u32 s14, s14, 0x8000
	s_addc_u32 s15, s15, 0
	s_waitcnt vmcnt(47)
	v_lshlrev_b32_e32 v212, 16, v224
	v_and_b32_e32 v213, 0xffff0000, v224
	v_lshlrev_b32_e32 v214, 16, v225
	v_and_b32_e32 v215, 0xffff0000, v225
	s_waitcnt vmcnt(46)
	v_pk_fma_f32 v[208:209], v[208:209], v[84:85], v[212:213]
	v_pk_fma_f32 v[210:211], v[210:211], v[86:87], v[214:215]
	v_cvt_pk_bf16_f32 v216, v208, v209
	v_cvt_pk_bf16_f32 v217, v210, v211
	global_store_dwordx2 v220, v[216:217], s[14:15]
	s_add_u32 s14, s14, 0x8000
	s_addc_u32 s15, s15, 0
	s_waitcnt vmcnt(46)
	v_lshlrev_b32_e32 v212, 16, v200
	v_and_b32_e32 v213, 0xffff0000, v200
	v_lshlrev_b32_e32 v214, 16, v201
	v_and_b32_e32 v215, 0xffff0000, v201
	s_waitcnt vmcnt(45)
	v_pk_fma_f32 v[208:209], v[208:209], v[88:89], v[212:213]
	v_pk_fma_f32 v[210:211], v[210:211], v[90:91], v[214:215]
	v_cvt_pk_bf16_f32 v218, v208, v209
	v_cvt_pk_bf16_f32 v219, v210, v211
	global_store_dwordx2 v220, v[218:219], s[14:15]
	s_add_u32 s14, s14, 0x8000
	s_addc_u32 s15, s15, 0
	s_waitcnt vmcnt(45)
	v_lshlrev_b32_e32 v212, 16, v202
	v_and_b32_e32 v213, 0xffff0000, v202
	v_lshlrev_b32_e32 v214, 16, v203
	v_and_b32_e32 v215, 0xffff0000, v203
	s_waitcnt vmcnt(44)
	v_pk_fma_f32 v[208:209], v[208:209], v[92:93], v[212:213]
	v_pk_fma_f32 v[210:211], v[210:211], v[94:95], v[214:215]
	v_cvt_pk_bf16_f32 v216, v208, v209
	v_cvt_pk_bf16_f32 v217, v210, v211
	global_store_dwordx2 v220, v[216:217], s[14:15]
	s_add_u32 s14, s14, 0x8000
	s_addc_u32 s15, s15, 0
	s_waitcnt vmcnt(44)
	v_lshlrev_b32_e32 v212, 16, v204
	v_and_b32_e32 v213, 0xffff0000, v204
	v_lshlrev_b32_e32 v214, 16, v205
	v_and_b32_e32 v215, 0xffff0000, v205
	s_waitcnt vmcnt(43)
	v_pk_fma_f32 v[208:209], v[208:209], v[100:101], v[212:213]
	v_pk_fma_f32 v[210:211], v[210:211], v[102:103], v[214:215]
	v_cvt_pk_bf16_f32 v218, v208, v209
	v_cvt_pk_bf16_f32 v219, v210, v211
	global_store_dwordx2 v220, v[218:219], s[14:15]
	s_add_u32 s14, s14, 0x8000
	s_addc_u32 s15, s15, 0
	s_waitcnt vmcnt(43)
	v_lshlrev_b32_e32 v212, 16, v206
	v_and_b32_e32 v213, 0xffff0000, v206
	v_lshlrev_b32_e32 v214, 16, v207
	v_and_b32_e32 v215, 0xffff0000, v207
	s_waitcnt vmcnt(42)
	v_pk_fma_f32 v[208:209], v[208:209], v[104:105], v[212:213]
	v_pk_fma_f32 v[210:211], v[210:211], v[106:107], v[214:215]
	v_cvt_pk_bf16_f32 v216, v208, v209
	v_cvt_pk_bf16_f32 v217, v210, v211
	global_store_dwordx2 v220, v[216:217], s[14:15]
	s_add_u32 s14, s14, 0x8000
	s_addc_u32 s15, s15, 0
	s_waitcnt vmcnt(42)
; __device__ __forceinline__ unsigned pk2(float lo, float hi) { f32x2_t v = {lo, hi}; bf16x2_t b = __builtin_convertvector(v, bf16x2_t); return __builtin_bit_cast(unsigned, b); }
; __device__ __forceinline__ float bflo(unsigned u) { return __uint_as_float(u << 16); }
; __device__ __forceinline__ float bfhi(unsigned u) { return __uint_as_float(u & 0xffff0000u); }
; #define SEAM(k) do { if (IN(k) && IN((k) + 1)) { if (a.pad == 0x5eed) cg::this_grid().sync(); xcd_barrier(xbar); } } while (0)
; __device__ __forceinline__ void hgrn_scan_phase(const Args& a) {
;     ...
;         for (int c = 0; c < 32; ++c) {
;             const u32x2 u = st[(size_t)c * 4096]; const f32x4 dd = dc[c * 32];
;             u32x2 o; o.x = pk2(r0, r1); o.y = pk2(r2, r3); st[(size_t)c * 4096] = o;
;             r0 = dd.x * r0 + bflo(u.x); r1 = dd.y * r1 + bfhi(u.x); r2 = dd.z * r2 + bflo(u.y); r3 = dd.w * r3 + bfhi(u.y);
;         }
;     }
; }
; __global__ void __launch_bounds__(512) hymba_fwd(Args a) {
;     ...
;             hgrn_scan_phase(a);
;             __syncthreads();
;         }
;         SEAM(base + 2);
	v_lshlrev_b32_e32 v212, 16, v226
	v_and_b32_e32 v213, 0xffff0000, v226
	v_lshlrev_b32_e32 v214, 16, v227
	v_and_b32_e32 v215, 0xffff0000, v227
	s_waitcnt vmcnt(41)
	v_pk_fma_f32 v[208:209], v[208:209], v[108:109], v[212:213]
	v_pk_fma_f32 v[210:211], v[210:211], v[110:111], v[214:215]
	v_cvt_pk_bf16_f32 v218, v208, v209
	v_cvt_pk_bf16_f32 v219, v210, v211
	global_store_dwordx2 v220, v[218:219], s[14:15]
	s_add_u32 s14, s14, 0x8000
	s_addc_u32 s15, s15, 0
	s_waitcnt vmcnt(41)
	v_lshlrev_b32_e32 v212, 16, v228
	v_and_b32_e32 v213, 0xffff0000, v228
	v_lshlrev_b32_e32 v214, 16, v229
	v_and_b32_e32 v215, 0xffff0000, v229
	s_waitcnt vmcnt(40)
	v_pk_fma_f32 v[208:209], v[208:209], v[112:113], v[212:213]
	v_pk_fma_f32 v[210:211], v[210:211], v[114:115], v[214:215]
	v_cvt_pk_bf16_f32 v216, v208, v209
	v_cvt_pk_bf16_f32 v217, v210, v211
	global_store_dwordx2 v220, v[216:217], s[14:15]
	s_add_u32 s14, s14, 0x8000
	s_addc_u32 s15, s15, 0
	s_waitcnt vmcnt(39)
	v_lshlrev_b32_e32 v212, 16, v128
	v_and_b32_e32 v213, 0xffff0000, v128
	v_lshlrev_b32_e32 v214, 16, v129
	v_and_b32_e32 v215, 0xffff0000, v129
	s_waitcnt vmcnt(38)
	v_pk_fma_f32 v[208:209], v[208:209], v[12:13], v[212:213]
	v_pk_fma_f32 v[210:211], v[210:211], v[14:15], v[214:215]
	v_cvt_pk_bf16_f32 v218, v208, v209
	v_cvt_pk_bf16_f32 v219, v210, v211
	global_store_dwordx2 v220, v[218:219], s[14:15]
	s_add_u32 s14, s14, 0x8000
	s_addc_u32 s15, s15, 0
	s_waitcnt vmcnt(37)
	v_lshlrev_b32_e32 v212, 16, v130
	v_and_b32_e32 v213, 0xffff0000, v130
	v_lshlrev_b32_e32 v214, 16, v131
	v_and_b32_e32 v215, 0xffff0000, v131
	s_waitcnt vmcnt(36)
	v_pk_fma_f32 v[208:209], v[208:209], v[16:17], v[212:213]
	v_pk_fma_f32 v[210:211], v[210:211], v[18:19], v[214:215]
	v_cvt_pk_bf16_f32 v216, v208, v209
	v_cvt_pk_bf16_f32 v217, v210, v211
	global_store_dwordx2 v220, v[216:217], s[14:15]
	s_add_u32 s14, s14, 0x8000
	s_addc_u32 s15, s15, 0
	s_waitcnt vmcnt(35)
	v_lshlrev_b32_e32 v212, 16, v132
	v_and_b32_e32 v213, 0xffff0000, v132
	v_lshlrev_b32_e32 v214, 16, v133
	v_and_b32_e32 v215, 0xffff0000, v133
	s_waitcnt vmcnt(34)
	v_pk_fma_f32 v[208:209], v[208:209], v[20:21], v[212:213]
	v_pk_fma_f32 v[210:211], v[210:211], v[22:23], v[214:215]
	v_cvt_pk_bf16_f32 v218, v208, v209
	v_cvt_pk_bf16_f32 v219, v210, v211
	global_store_dwordx2 v220, v[218:219], s[14:15]
	s_add_u32 s14, s14, 0x8000
	s_addc_u32 s15, s15, 0
	s_waitcnt vmcnt(33)
	v_lshlrev_b32_e32 v212, 16, v134
	v_and_b32_e32 v213, 0xffff0000, v134
	v_lshlrev_b32_e32 v214, 16, v135
	v_and_b32_e32 v215, 0xffff0000, v135
	s_waitcnt vmcnt(32)
	v_pk_fma_f32 v[208:209], v[208:209], v[24:25], v[212:213]
	v_pk_fma_f32 v[210:211], v[210:211], v[26:27], v[214:215]
	v_cvt_pk_bf16_f32 v216, v208, v209
	v_cvt_pk_bf16_f32 v217, v210, v211
	global_store_dwordx2 v220, v[216:217], s[14:15]
	s_add_u32 s14, s14, 0x8000
	s_addc_u32 s15, s15, 0
	s_waitcnt vmcnt(31)
	v_lshlrev_b32_e32 v212, 16, v136
	v_and_b32_e32 v213, 0xffff0000, v136
	v_lshlrev_b32_e32 v214, 16, v137
	v_and_b32_e32 v215, 0xffff0000, v137
	s_waitcnt vmcnt(30)
	v_pk_fma_f32 v[208:209], v[208:209], v[28:29], v[212:213]
	v_pk_fma_f32 v[210:211], v[210:211], v[30:31], v[214:215]
	v_cvt_pk_bf16_f32 v218, v208, v209
	v_cvt_pk_bf16_f32 v219, v210, v211
	global_store_dwordx2 v220, v[218:219], s[14:15]
	s_add_u32 s14, s14, 0x8000
	s_addc_u32 s15, s15, 0
	s_waitcnt vmcnt(29)
	v_lshlrev_b32_e32 v212, 16, v138
	v_and_b32_e32 v213, 0xffff0000, v138
	v_lshlrev_b32_e32 v214, 16, v139
	v_and_b32_e32 v215, 0xffff0000, v139
	s_waitcnt vmcnt(28)
	v_pk_fma_f32 v[208:209], v[208:209], v[32:33], v[212:213]
	v_pk_fma_f32 v[210:211], v[210:211], v[34:35], v[214:215]
	v_cvt_pk_bf16_f32 v216, v208, v209
	v_cvt_pk_bf16_f32 v217, v210, v211
	global_store_dwordx2 v220, v[216:217], s[14:15]
	s_add_u32 s14, s14, 0x8000
	s_addc_u32 s15, s15, 0
	s_waitcnt vmcnt(27)
	v_lshlrev_b32_e32 v212, 16, v140
	v_and_b32_e32 v213, 0xffff0000, v140
	v_lshlrev_b32_e32 v214, 16, v141
	v_and_b32_e32 v215, 0xffff0000, v141
	s_waitcnt vmcnt(26)
	v_pk_fma_f32 v[208:209], v[208:209], v[36:37], v[212:213]
	v_pk_fma_f32 v[210:211], v[210:211], v[38:39], v[214:215]
	v_cvt_pk_bf16_f32 v218, v208, v209
	v_cvt_pk_bf16_f32 v219, v210, v211
	global_store_dwordx2 v220, v[218:219], s[14:15]
	s_add_u32 s14, s14, 0x8000
	s_addc_u32 s15, s15, 0
	s_waitcnt vmcnt(25)
	v_lshlrev_b32_e32 v212, 16, v142
	v_and_b32_e32 v213, 0xffff0000, v142
	v_lshlrev_b32_e32 v214, 16, v143
	v_and_b32_e32 v215, 0xffff0000, v143
	s_waitcnt vmcnt(24)
	v_pk_fma_f32 v[208:209], v[208:209], v[40:41], v[212:213]
	v_pk_fma_f32 v[210:211], v[210:211], v[42:43], v[214:215]
	s_branch .LBB0_527
.Lx2_ret:
	s_mov_b32 s98, 2
	s_branch .Lx2_back

; __global__ void __launch_bounds__(512) hymba_fwd(Args a) {
	.amdhsa_kernel _Z9hymba_fwd4Args
		.amdhsa_group_segment_fixed_size 0
		.amdhsa_private_segment_fixed_size 0
		.amdhsa_kernarg_size 400
		.amdhsa_user_sgpr_count 2
		.amdhsa_user_sgpr_dispatch_ptr 0
		.amdhsa_user_sgpr_queue_ptr 0
		.amdhsa_user_sgpr_kernarg_segment_ptr 1
		.amdhsa_user_sgpr_dispatch_id 0
		.amdhsa_user_sgpr_kernarg_preload_length 0
		.amdhsa_user_sgpr_kernarg_preload_offset 0
		.amdhsa_user_sgpr_private_segment_size 0
		.amdhsa_uses_dynamic_stack 0
		.amdhsa_enable_private_segment 0
		.amdhsa_system_sgpr_workgroup_id_x 1
		.amdhsa_system_sgpr_workgroup_id_y 0
		.amdhsa_system_sgpr_workgroup_id_z 0
		.amdhsa_system_sgpr_workgroup_info 0
		.amdhsa_system_vgpr_workitem_id 2
		.amdhsa_next_free_vgpr 248
		.amdhsa_next_free_sgpr 99
		.amdhsa_accum_offset 248
		.amdhsa_reserve_vcc 1
		.amdhsa_float_round_mode_32 0
		.amdhsa_float_round_mode_16_64 0
		.amdhsa_float_denorm_mode_32 3
		.amdhsa_float_denorm_mode_16_64 3
		.amdhsa_dx10_clamp 1
		.amdhsa_ieee_mode 1
		.amdhsa_fp16_overflow 0
		.amdhsa_tg_split 0
		.amdhsa_exception_fp_ieee_invalid_op 0
		.amdhsa_exception_fp_denorm_src 0
		.amdhsa_exception_fp_ieee_div_zero 0
		.amdhsa_exception_fp_ieee_overflow 0
		.amdhsa_exception_fp_ieee_underflow 0
		.amdhsa_exception_fp_ieee_inexact 0
		.amdhsa_exception_int_div_zero 0
	.end_amdhsa_kernel

; __global__ void __launch_bounds__(512) hymba_fwd(Args a) {
amdhsa.kernels:
  - .agpr_count:     0
    .args:
      - .offset:         0
        .size:           144
        .value_kind:     by_value
      - .offset:         144
        .size:           4
        .value_kind:     hidden_block_count_x
      - .offset:         148
        .size:           4
        .value_kind:     hidden_block_count_y
      - .offset:         152
        .size:           4
        .value_kind:     hidden_block_count_z
      - .offset:         156
        .size:           2
        .value_kind:     hidden_group_size_x
      - .offset:         158
        .size:           2
        .value_kind:     hidden_group_size_y
      - .offset:         160
        .size:           2
        .value_kind:     hidden_group_size_z
      - .offset:         162
        .size:           2
        .value_kind:     hidden_remainder_x
      - .offset:         164
        .size:           2
        .value_kind:     hidden_remainder_y
      - .offset:         166
        .size:           2
        .value_kind:     hidden_remainder_z
      - .offset:         184
        .size:           8
        .value_kind:     hidden_global_offset_x
      - .offset:         192
        .size:           8
        .value_kind:     hidden_global_offset_y
      - .offset:         200
        .size:           8
        .value_kind:     hidden_global_offset_z
      - .offset:         208
        .size:           2
        .value_kind:     hidden_grid_dims
      - .offset:         232
        .size:           8
        .value_kind:     hidden_multigrid_sync_arg
      - .offset:         264
        .size:           4
        .value_kind:     hidden_dynamic_lds_size
    .group_segment_fixed_size: 0
    .kernarg_segment_align: 8
    .kernarg_segment_size: 400
    .language:       OpenCL C
    .language_version:
      - 2
      - 0
    .max_flat_workgroup_size: 512
    .name:           _Z9hymba_fwd4Args
    .private_segment_fixed_size: 0
    .sgpr_count:     105
    .sgpr_spill_count: 193
    .symbol:         _Z9hymba_fwd4Args.kd
    .uniform_work_group_size: 1
    .uses_dynamic_stack: false
    .vgpr_count:     248
    .vgpr_spill_count: 0
    .wavefront_size: 64
